# v18 stack + GEMM K-loop heads aligned to 64 B
# speedup vs baseline: 1.0001x; 1.0001x over previous
.LBB0_13:
	s_lshr_b32 s13, s12, 4
	s_and_b32 s13, s13, 24
	s_and_b32 s14, s12, 7
	s_or_b32 s13, s13, s14
	s_lshl_b32 s13, s13, 10
	v_mov_b32 v8, v198
	s_or_b32 s14, s13, s65
	v_ashrrev_i32_e32 v12, 2, v8
	v_add_u32_e32 v0, s14, v12
	v_ashrrev_i32_e32 v1, 31, v0
	v_readlane_b32 s16, v253, 21
	s_lshl_b32 s15, s12, 5
	v_lshlrev_b64 v[0:1], 11, v[0:1]
	v_readlane_b32 s17, v253, 22
	v_lshlrev_b32_e32 v2, 4, v8
	s_and_b32 s13, s15, 0xf00
	v_lshl_add_u64 v[0:1], s[16:17], 0, v[0:1]
	v_and_b32_e32 v152, 48, v2
	v_lshl_add_u64 v[14:15], v[0:1], 0, v[152:153]
	v_add_u32_e32 v0, s13, v12
	v_ashrrev_i32_e32 v1, 31, v0
	v_lshlrev_b64 v[0:1], 11, v[0:1]
	v_lshl_add_u64 v[0:1], s[4:5], 0, v[0:1]
	v_add_co_u32_e32 v54, vcc, s62, v14
	v_lshl_add_u64 v[0:1], v[0:1], 0, v[152:153]
	s_nop 0
	v_addc_co_u32_e32 v55, vcc, 0, v15, vcc
	s_lshl_b32 s16, s11, 11
	s_lshl_b32 s17, s12, 6
	s_and_b32 s18, s10, 7
	v_add_co_u32_e32 v2, vcc, s62, v0
	s_and_b32 s16, s16, 0x780000
	s_and_b32 s19, s17, 0x6000
	s_lshl_b32 s18, s18, 10
	v_lshrrev_b32_e32 v6, 2, v8
	v_addc_co_u32_e32 v3, vcc, 0, v1, vcc
	v_and_b32_e32 v6, 12, v6
	v_ashrrev_i32_e32 v13, 31, v12
	s_movk_i32 s17, 0x1230
	s_add_u32 s16, s7, s16
	v_add_co_u32_e32 v4, vcc, s33, v0
	v_lshrrev_b32_e64 v10, v6, s17
	v_lshlrev_b64 v[6:7], 11, v[12:13]
	s_addc_u32 s17, s8, 0
	s_or_b32 s18, s18, s19
	v_addc_co_u32_e32 v5, vcc, 0, v1, vcc
	v_and_b32_e32 v22, 3, v8
	v_xor_b32_e32 v8, v10, v8
	v_lshl_add_u64 v[156:157], s[16:17], 0, v[6:7]
	s_or_b32 s16, s18, s65
	v_add_co_u32_e32 v20, vcc, s72, v0
	v_lshlrev_b32_e32 v9, 6, v12
	v_lshlrev_b32_e32 v8, 4, v8
	v_add_u32_e32 v12, s16, v12
	v_addc_co_u32_e32 v21, vcc, 0, v1, vcc
	s_nop 0
	v_readfirstlane_b32 s26, v14
	v_readfirstlane_b32 s27, v15
	v_readfirstlane_b32 s28, v0
	v_readfirstlane_b32 s29, v1
	v_lshrrev_b32_e32 v250, 6, v198
	s_nop 0
	v_readfirstlane_b32 s24, v250
	s_lshl_b32 s24, s24, 10
	v_lshrrev_b32_e32 v250, 2, v200
	v_lshrrev_b32_e32 v251, 4, v200
	v_lshlrev_b32_e32 v251, 2, v251
	v_mov_b32_e32 v248, 0x1230
	v_lshrrev_b32_e32 v251, v251, v248
	v_xor_b32_e32 v251, v251, v200
	v_and_b32_e32 v251, 3, v251
	v_lshlrev_b32_e32 v251, 4, v251
	v_lshl_add_u32 v244, v250, 11, v251
	v_add_u32_e32 v245, 0x20000, v244
	v_add_u32_e32 v246, 0x40000, v244
	v_add_u32_e32 v247, 0x60000, v244
	s_mov_b32 s25, 0
	s_add_u32 m0, s25, s24
	s_nop 0
	global_load_lds_dwordx4 v244, s[26:27]
	s_add_u32 m0, m0, 0x1000
	s_nop 0
	global_load_lds_dwordx4 v245, s[26:27]
	s_add_u32 m0, m0, 0x1000
	s_nop 0
	global_load_lds_dwordx4 v244, s[28:29]
	s_add_u32 m0, m0, 0x1000
	s_nop 0
	global_load_lds_dwordx4 v245, s[28:29]
	s_add_u32 m0, m0, 0x1000
	s_nop 0
	global_load_lds_dwordx4 v246, s[28:29]
	s_add_u32 m0, m0, 0x1000
	s_nop 0
	global_load_lds_dwordx4 v247, s[28:29]
	s_add_u32 s26, s26, 64
	s_addc_u32 s27, s27, 0
	s_add_u32 s28, s28, 64
	s_addc_u32 s29, s29, 0
	s_add_u32 s25, s25, 24576
	s_cmp_eq_u32 s25, 73728
	s_cselect_b32 s25, 0, s25
	s_add_u32 m0, s25, s24
	s_nop 0
	global_load_lds_dwordx4 v244, s[26:27]
	s_add_u32 m0, m0, 0x1000
	s_nop 0
	global_load_lds_dwordx4 v245, s[26:27]
	s_add_u32 m0, m0, 0x1000
	s_nop 0
	global_load_lds_dwordx4 v244, s[28:29]
	s_add_u32 m0, m0, 0x1000
	s_nop 0
	global_load_lds_dwordx4 v245, s[28:29]
	s_add_u32 m0, m0, 0x1000
	s_nop 0
	global_load_lds_dwordx4 v246, s[28:29]
	s_add_u32 m0, m0, 0x1000
	s_nop 0
	global_load_lds_dwordx4 v247, s[28:29]
	s_add_u32 s26, s26, 64
	s_addc_u32 s27, s27, 0
	s_add_u32 s28, s28, 64
	s_addc_u32 s29, s29, 0
	s_add_u32 s25, s25, 24576
	s_cmp_eq_u32 s25, 73728
	s_cselect_b32 s25, 0, s25
	s_add_u32 m0, s25, s24
	s_nop 0
	global_load_lds_dwordx4 v244, s[26:27]
	s_add_u32 m0, m0, 0x1000
	s_nop 0
	global_load_lds_dwordx4 v245, s[26:27]
	s_add_u32 m0, m0, 0x1000
	s_nop 0
	global_load_lds_dwordx4 v244, s[28:29]
	s_add_u32 m0, m0, 0x1000
	s_nop 0
	global_load_lds_dwordx4 v245, s[28:29]
	s_add_u32 m0, m0, 0x1000
	s_nop 0
	global_load_lds_dwordx4 v246, s[28:29]
	s_add_u32 m0, m0, 0x1000
	s_nop 0
	global_load_lds_dwordx4 v247, s[28:29]
	s_add_u32 s26, s26, 64
	s_addc_u32 s27, s27, 0
	s_add_u32 s28, s28, 64
	s_addc_u32 s29, s29, 0
	s_add_u32 s25, s25, 24576
	s_cmp_eq_u32 s25, 73728
	s_cselect_b32 s25, 0, s25
	v_mov_b32_e32 v24, 0
	v_mov_b32_e32 v25, v24
	v_mov_b32_e32 v26, v24
	v_mov_b32_e32 v27, v24
	v_mov_b32_e32 v28, v24
	v_mov_b32_e32 v29, v24
	v_mov_b32_e32 v84, v24
	v_mov_b32_e32 v85, v24
	v_mov_b32_e32 v86, v24
	v_mov_b32_e32 v87, v24
	v_mov_b32_e32 v88, v24
	v_mov_b32_e32 v89, v24
	v_mov_b32_e32 v90, v24
	v_mov_b32_e32 v91, v24
	v_mov_b32_e32 v92, v24
	v_mov_b32_e32 v93, v24
	v_mov_b32_e32 v94, v24
	v_mov_b32_e32 v95, v24
	v_mov_b32_e32 v96, v24
	v_mov_b32_e32 v97, v24
	v_mov_b32_e32 v98, v24
	v_mov_b32_e32 v99, v24
	v_mov_b32_e32 v54, v24
	v_mov_b32_e32 v55, v24
	v_mov_b32_e32 v100, v24
	v_mov_b32_e32 v101, v24
	v_mov_b32_e32 v30, v24
	v_mov_b32_e32 v31, v24
	v_mov_b32_e32 v32, v24
	v_mov_b32_e32 v33, v24
	v_mov_b32_e32 v34, v24
	v_mov_b32_e32 v35, v24
	v_mov_b32_e32 v36, v24
	v_mov_b32_e32 v37, v24
	v_mov_b32_e32 v38, v24
	v_mov_b32_e32 v39, v24
	v_mov_b32_e32 v40, v24
	v_mov_b32_e32 v41, v24
	v_mov_b32_e32 v42, v24
	v_mov_b32_e32 v43, v24
	v_mov_b32_e32 v44, v24
	v_mov_b32_e32 v45, v24
	v_mov_b32_e32 v46, v24
	v_mov_b32_e32 v47, v24
	v_mov_b32_e32 v48, v24
	v_mov_b32_e32 v49, v24
	v_mov_b32_e32 v50, v24
	v_mov_b32_e32 v51, v24
	v_mov_b32_e32 v52, v24
	v_mov_b32_e32 v53, v24
	v_mov_b32_e32 v102, v24
	v_mov_b32_e32 v103, v24
	v_mov_b32_e32 v104, v24
	v_mov_b32_e32 v105, v24
	v_mov_b32_e32 v106, v24
	v_mov_b32_e32 v107, v24
	v_mov_b32_e32 v116, v24
	v_mov_b32_e32 v117, v24
	v_mov_b32_e32 v118, v24
	v_mov_b32_e32 v119, v24
	v_mov_b32_e32 v128, v24
	v_mov_b32_e32 v129, v24
	v_mov_b32_e32 v130, v24
	v_mov_b32_e32 v131, v24
	v_mov_b32_e32 v108, v24
	v_mov_b32_e32 v109, v24
	v_mov_b32_e32 v110, v24
	v_mov_b32_e32 v111, v24
	v_mov_b32_e32 v112, v24
	v_mov_b32_e32 v113, v24
	v_mov_b32_e32 v114, v24
	v_mov_b32_e32 v115, v24
	v_mov_b32_e32 v120, v24
	v_mov_b32_e32 v121, v24
	v_mov_b32_e32 v122, v24
	v_mov_b32_e32 v123, v24
	v_mov_b32_e32 v124, v24
	v_mov_b32_e32 v125, v24
	v_mov_b32_e32 v126, v24
	v_mov_b32_e32 v127, v24
	v_mov_b32_e32 v64, v24
	v_mov_b32_e32 v65, v24
	v_mov_b32_e32 v66, v24
	v_mov_b32_e32 v67, v24
	v_mov_b32_e32 v68, v24
	v_mov_b32_e32 v69, v24
	v_mov_b32_e32 v70, v24
	v_mov_b32_e32 v71, v24
	v_mov_b32_e32 v80, v24
	v_mov_b32_e32 v81, v24
	v_mov_b32_e32 v82, v24
	v_mov_b32_e32 v83, v24
	v_mov_b32_e32 v56, v24
	v_mov_b32_e32 v57, v24
	v_mov_b32_e32 v58, v24
	v_mov_b32_e32 v59, v24
	v_mov_b32_e32 v132, v24
	v_mov_b32_e32 v133, v24
	v_mov_b32_e32 v134, v24
	v_mov_b32_e32 v135, v24
	v_mov_b32_e32 v136, v24
	v_mov_b32_e32 v137, v24
	v_mov_b32_e32 v138, v24
	v_mov_b32_e32 v139, v24
	v_mov_b32_e32 v140, v24
	v_mov_b32_e32 v141, v24
	v_mov_b32_e32 v142, v24
	v_mov_b32_e32 v143, v24
	v_mov_b32_e32 v144, v24
	v_mov_b32_e32 v145, v24
	v_mov_b32_e32 v146, v24
	v_mov_b32_e32 v147, v24
	v_mov_b32_e32 v76, v24
	v_mov_b32_e32 v77, v24
	v_mov_b32_e32 v78, v24
	v_mov_b32_e32 v79, v24
	v_mov_b32_e32 v72, v24
	v_mov_b32_e32 v73, v24
	v_mov_b32_e32 v74, v24
	v_mov_b32_e32 v75, v24
	v_mov_b32_e32 v60, v24
	v_mov_b32_e32 v61, v24
	v_mov_b32_e32 v62, v24
	v_mov_b32_e32 v63, v24
	v_mov_b32_e32 v148, v24
	v_mov_b32_e32 v149, v24
	v_mov_b32_e32 v150, v24
	v_mov_b32_e32 v151, v24
	s_waitcnt vmcnt(12)
	s_barrier
	s_mov_b32 s30, 0
	v_add_u32_e32 v248, s30, v155
	v_add_u32_e32 v249, s30, v160
	ds_read_b128 v[186:189], v248
	ds_read_b128 v[212:215], v249 offset:8192
	ds_read_b128 v[190:193], v248 offset:1024
	ds_read_b128 v[216:219], v249 offset:9216
	ds_read_b128 v[194:197], v248 offset:2048
	ds_read_b128 v[220:223], v249 offset:10240
	ds_read_b128 v[208:211], v248 offset:3072
	ds_read_b128 v[224:227], v249 offset:11264
	ds_read_b128 v[228:231], v249 offset:12288
	ds_read_b128 v[232:235], v249 offset:13312
	ds_read_b128 v[236:239], v249 offset:14336
	ds_read_b128 v[240:243], v249 offset:15360
	s_add_u32 s30, s30, 24576
	s_cmp_eq_u32 s30, 73728
	s_cselect_b32 s30, 0, s30
	s_waitcnt vmcnt(6)
	s_waitcnt lgkmcnt(0)
	s_barrier
	s_mov_b32 s31, 14
	.p2alignl 6, 3212836864

.LBB0_24:
	s_lshr_b32 s10, s18, 2
	s_and_b32 s10, s10, 24
	s_and_b32 s11, s18, 7
	s_or_b32 s10, s10, s11
	s_lshl_b32 s10, s10, 10
	v_mov_b32 v8, v198
	s_or_b32 s10, s10, s65
	v_ashrrev_i32_e32 v12, 2, v8
	v_add_u32_e32 v0, s10, v12
	s_waitcnt lgkmcnt(0)
	v_ashrrev_i32_e32 v1, 31, v0
	s_lshl_b32 s11, s18, 5
	v_lshlrev_b64 v[0:1], 11, v[0:1]
	v_lshlrev_b32_e32 v2, 4, v8
	s_and_b32 s11, s11, 0x300
	v_lshl_add_u64 v[0:1], s[96:97], 0, v[0:1]
	v_and_b32_e32 v152, 48, v2
	v_lshl_add_u64 v[14:15], v[0:1], 0, v[152:153]
	v_add_u32_e32 v0, s11, v12
	v_ashrrev_i32_e32 v1, 31, v0
	v_lshlrev_b64 v[0:1], 11, v[0:1]
	v_lshl_add_u64 v[0:1], s[4:5], 0, v[0:1]
	v_add_co_u32_e32 v54, vcc, s62, v14
	v_lshl_add_u64 v[0:1], v[0:1], 0, v[152:153]
	s_nop 0
	v_addc_co_u32_e32 v55, vcc, 0, v15, vcc
	s_lshl_b32 s20, s17, 11
	s_lshl_b32 s21, s18, 8
	s_and_b32 s22, s16, 7
	v_add_co_u32_e32 v2, vcc, s62, v0
	s_and_b32 s20, s20, 0x180000
	s_and_b32 s23, s21, 0x6000
	s_lshl_b32 s22, s22, 10
	v_lshrrev_b32_e32 v6, 2, v8
	v_addc_co_u32_e32 v3, vcc, 0, v1, vcc
	v_and_b32_e32 v6, 12, v6
	v_ashrrev_i32_e32 v13, 31, v12
	s_movk_i32 s21, 0x1230
	s_add_u32 s20, s13, s20
	v_add_co_u32_e32 v4, vcc, s33, v0
	v_lshrrev_b32_e64 v10, v6, s21
	v_lshlrev_b64 v[6:7], 11, v[12:13]
	s_addc_u32 s21, s14, 0
	s_or_b32 s22, s22, s23
	v_addc_co_u32_e32 v5, vcc, 0, v1, vcc
	v_and_b32_e32 v22, 3, v8
	v_xor_b32_e32 v8, v10, v8
	v_lshl_add_u64 v[156:157], s[20:21], 0, v[6:7]
	s_or_b32 s20, s22, s65
	v_add_co_u32_e32 v20, vcc, s72, v0
	v_lshlrev_b32_e32 v9, 6, v12
	v_lshlrev_b32_e32 v8, 4, v8
	v_add_u32_e32 v12, s20, v12
	v_addc_co_u32_e32 v21, vcc, 0, v1, vcc
	s_nop 0
	v_readfirstlane_b32 s26, v14
	v_readfirstlane_b32 s27, v15
	v_readfirstlane_b32 s28, v0
	v_readfirstlane_b32 s29, v1
	v_lshrrev_b32_e32 v250, 6, v198
	s_nop 0
	v_readfirstlane_b32 s24, v250
	s_lshl_b32 s24, s24, 10
	v_lshrrev_b32_e32 v250, 2, v200
	v_lshrrev_b32_e32 v251, 4, v200
	v_lshlrev_b32_e32 v251, 2, v251
	v_mov_b32_e32 v248, 0x1230
	v_lshrrev_b32_e32 v251, v251, v248
	v_xor_b32_e32 v251, v251, v200
	v_and_b32_e32 v251, 3, v251
	v_lshlrev_b32_e32 v251, 4, v251
	v_lshl_add_u32 v244, v250, 11, v251
	v_add_u32_e32 v245, 0x20000, v244
	v_add_u32_e32 v246, 0x40000, v244
	v_add_u32_e32 v247, 0x60000, v244
	s_mov_b32 s25, 0
	s_add_u32 m0, s25, s24
	s_nop 0
	global_load_lds_dwordx4 v244, s[26:27]
	s_add_u32 m0, m0, 0x1000
	s_nop 0
	global_load_lds_dwordx4 v245, s[26:27]
	s_add_u32 m0, m0, 0x1000
	s_nop 0
	global_load_lds_dwordx4 v244, s[28:29]
	s_add_u32 m0, m0, 0x1000
	s_nop 0
	global_load_lds_dwordx4 v245, s[28:29]
	s_add_u32 m0, m0, 0x1000
	s_nop 0
	global_load_lds_dwordx4 v246, s[28:29]
	s_add_u32 m0, m0, 0x1000
	s_nop 0
	global_load_lds_dwordx4 v247, s[28:29]
	s_add_u32 s26, s26, 64
	s_addc_u32 s27, s27, 0
	s_add_u32 s28, s28, 64
	s_addc_u32 s29, s29, 0
	s_add_u32 s25, s25, 24576
	s_cmp_eq_u32 s25, 73728
	s_cselect_b32 s25, 0, s25
	s_add_u32 m0, s25, s24
	s_nop 0
	global_load_lds_dwordx4 v244, s[26:27]
	s_add_u32 m0, m0, 0x1000
	s_nop 0
	global_load_lds_dwordx4 v245, s[26:27]
	s_add_u32 m0, m0, 0x1000
	s_nop 0
	global_load_lds_dwordx4 v244, s[28:29]
	s_add_u32 m0, m0, 0x1000
	s_nop 0
	global_load_lds_dwordx4 v245, s[28:29]
	s_add_u32 m0, m0, 0x1000
	s_nop 0
	global_load_lds_dwordx4 v246, s[28:29]
	s_add_u32 m0, m0, 0x1000
	s_nop 0
	global_load_lds_dwordx4 v247, s[28:29]
	s_add_u32 s26, s26, 64
	s_addc_u32 s27, s27, 0
	s_add_u32 s28, s28, 64
	s_addc_u32 s29, s29, 0
	s_add_u32 s25, s25, 24576
	s_cmp_eq_u32 s25, 73728
	s_cselect_b32 s25, 0, s25
	s_add_u32 m0, s25, s24
	s_nop 0
	global_load_lds_dwordx4 v244, s[26:27]
	s_add_u32 m0, m0, 0x1000
	s_nop 0
	global_load_lds_dwordx4 v245, s[26:27]
	s_add_u32 m0, m0, 0x1000
	s_nop 0
	global_load_lds_dwordx4 v244, s[28:29]
	s_add_u32 m0, m0, 0x1000
	s_nop 0
	global_load_lds_dwordx4 v245, s[28:29]
	s_add_u32 m0, m0, 0x1000
	s_nop 0
	global_load_lds_dwordx4 v246, s[28:29]
	s_add_u32 m0, m0, 0x1000
	s_nop 0
	global_load_lds_dwordx4 v247, s[28:29]
	s_add_u32 s26, s26, 64
	s_addc_u32 s27, s27, 0
	s_add_u32 s28, s28, 64
	s_addc_u32 s29, s29, 0
	s_add_u32 s25, s25, 24576
	s_cmp_eq_u32 s25, 73728
	s_cselect_b32 s25, 0, s25
	v_mov_b32_e32 v24, 0
	v_mov_b32_e32 v25, v24
	v_mov_b32_e32 v26, v24
	v_mov_b32_e32 v27, v24
	v_mov_b32_e32 v28, v24
	v_mov_b32_e32 v29, v24
	v_mov_b32_e32 v60, v24
	v_mov_b32_e32 v61, v24
	v_mov_b32_e32 v62, v24
	v_mov_b32_e32 v63, v24
	v_mov_b32_e32 v64, v24
	v_mov_b32_e32 v65, v24
	v_mov_b32_e32 v66, v24
	v_mov_b32_e32 v67, v24
	v_mov_b32_e32 v72, v24
	v_mov_b32_e32 v73, v24
	v_mov_b32_e32 v74, v24
	v_mov_b32_e32 v75, v24
	v_mov_b32_e32 v80, v24
	v_mov_b32_e32 v81, v24
	v_mov_b32_e32 v82, v24
	v_mov_b32_e32 v83, v24
	v_mov_b32_e32 v56, v24
	v_mov_b32_e32 v57, v24
	v_mov_b32_e32 v58, v24
	v_mov_b32_e32 v59, v24
	v_mov_b32_e32 v68, v24
	v_mov_b32_e32 v69, v24
	v_mov_b32_e32 v30, v24
	v_mov_b32_e32 v31, v24
	v_mov_b32_e32 v32, v24
	v_mov_b32_e32 v33, v24
	v_mov_b32_e32 v34, v24
	v_mov_b32_e32 v35, v24
	v_mov_b32_e32 v36, v24
	v_mov_b32_e32 v37, v24
	v_mov_b32_e32 v38, v24
	v_mov_b32_e32 v39, v24
	v_mov_b32_e32 v40, v24
	v_mov_b32_e32 v41, v24
	v_mov_b32_e32 v42, v24
	v_mov_b32_e32 v43, v24
	v_mov_b32_e32 v48, v24
	v_mov_b32_e32 v49, v24
	v_mov_b32_e32 v50, v24
	v_mov_b32_e32 v51, v24
	v_mov_b32_e32 v70, v24
	v_mov_b32_e32 v71, v24
	v_mov_b32_e32 v100, v24
	v_mov_b32_e32 v101, v24
	v_mov_b32_e32 v102, v24
	v_mov_b32_e32 v103, v24
	v_mov_b32_e32 v104, v24
	v_mov_b32_e32 v105, v24
	v_mov_b32_e32 v106, v24
	v_mov_b32_e32 v107, v24
	v_mov_b32_e32 v120, v24
	v_mov_b32_e32 v121, v24
	v_mov_b32_e32 v122, v24
	v_mov_b32_e32 v123, v24
	v_mov_b32_e32 v128, v24
	v_mov_b32_e32 v129, v24
	v_mov_b32_e32 v130, v24
	v_mov_b32_e32 v131, v24
	v_mov_b32_e32 v108, v24
	v_mov_b32_e32 v109, v24
	v_mov_b32_e32 v110, v24
	v_mov_b32_e32 v111, v24
	v_mov_b32_e32 v112, v24
	v_mov_b32_e32 v113, v24
	v_mov_b32_e32 v114, v24
	v_mov_b32_e32 v115, v24
	v_mov_b32_e32 v116, v24
	v_mov_b32_e32 v117, v24
	v_mov_b32_e32 v118, v24
	v_mov_b32_e32 v119, v24
	v_mov_b32_e32 v124, v24
	v_mov_b32_e32 v125, v24
	v_mov_b32_e32 v126, v24
	v_mov_b32_e32 v127, v24
	v_mov_b32_e32 v88, v24
	v_mov_b32_e32 v89, v24
	v_mov_b32_e32 v90, v24
	v_mov_b32_e32 v91, v24
	v_mov_b32_e32 v92, v24
	v_mov_b32_e32 v93, v24
	v_mov_b32_e32 v94, v24
	v_mov_b32_e32 v95, v24
	v_mov_b32_e32 v96, v24
	v_mov_b32_e32 v97, v24
	v_mov_b32_e32 v98, v24
	v_mov_b32_e32 v99, v24
	v_mov_b32_e32 v84, v24
	v_mov_b32_e32 v85, v24
	v_mov_b32_e32 v86, v24
	v_mov_b32_e32 v87, v24
	v_mov_b32_e32 v132, v24
	v_mov_b32_e32 v133, v24
	v_mov_b32_e32 v134, v24
	v_mov_b32_e32 v135, v24
	v_mov_b32_e32 v136, v24
	v_mov_b32_e32 v137, v24
	v_mov_b32_e32 v138, v24
	v_mov_b32_e32 v139, v24
	v_mov_b32_e32 v140, v24
	v_mov_b32_e32 v141, v24
	v_mov_b32_e32 v142, v24
	v_mov_b32_e32 v143, v24
	v_mov_b32_e32 v144, v24
	v_mov_b32_e32 v145, v24
	v_mov_b32_e32 v146, v24
	v_mov_b32_e32 v147, v24
	v_mov_b32_e32 v76, v24
	v_mov_b32_e32 v77, v24
	v_mov_b32_e32 v78, v24
	v_mov_b32_e32 v79, v24
	v_mov_b32_e32 v52, v24
	v_mov_b32_e32 v53, v24
	v_mov_b32_e32 v54, v24
	v_mov_b32_e32 v55, v24
	v_mov_b32_e32 v44, v24
	v_mov_b32_e32 v45, v24
	v_mov_b32_e32 v46, v24
	v_mov_b32_e32 v47, v24
	v_mov_b32_e32 v148, v24
	v_mov_b32_e32 v149, v24
	v_mov_b32_e32 v150, v24
	v_mov_b32_e32 v151, v24
	s_waitcnt vmcnt(12)
	s_barrier
	s_mov_b32 s30, 0
	v_add_u32_e32 v248, s30, v155
	v_add_u32_e32 v249, s30, v160
	ds_read_b128 v[186:189], v248
	ds_read_b128 v[212:215], v249 offset:8192
	ds_read_b128 v[190:193], v248 offset:1024
	ds_read_b128 v[216:219], v249 offset:9216
	ds_read_b128 v[194:197], v248 offset:2048
	ds_read_b128 v[220:223], v249 offset:10240
	ds_read_b128 v[208:211], v248 offset:3072
	ds_read_b128 v[224:227], v249 offset:11264
	ds_read_b128 v[228:231], v249 offset:12288
	ds_read_b128 v[232:235], v249 offset:13312
	ds_read_b128 v[236:239], v249 offset:14336
	ds_read_b128 v[240:243], v249 offset:15360
	s_add_u32 s30, s30, 24576
	s_cmp_eq_u32 s30, 73728
	s_cselect_b32 s30, 0, s30
	s_waitcnt vmcnt(6)
	s_waitcnt lgkmcnt(0)
	s_barrier
	s_mov_b32 s31, 14
	.p2alignl 6, 3212836864

.LBB0_362:
	s_lshr_b32 s4, s20, 2
	s_and_b32 s4, s4, 24
	s_and_b32 s5, s20, 7
	s_or_b32 s4, s4, s5
	s_lshl_b32 s4, s4, 10
	v_mov_b32 v8, v198
	s_or_b32 s4, s4, s65
	v_ashrrev_i32_e32 v12, 2, v8
	v_add_u32_e32 v0, s4, v12
	s_waitcnt lgkmcnt(0)
	v_ashrrev_i32_e32 v1, 31, v0
	s_lshl_b32 s5, s20, 5
	v_lshlrev_b64 v[0:1], 13, v[0:1]
	v_lshlrev_b32_e32 v2, 4, v8
	s_and_b32 s5, s5, 0x300
	v_lshl_add_u64 v[0:1], s[92:93], 0, v[0:1]
	v_and_b32_e32 v152, 48, v2
	v_lshl_add_u64 v[14:15], v[0:1], 0, v[152:153]
	v_add_u32_e32 v0, s5, v12
	v_ashrrev_i32_e32 v1, 31, v0
	v_lshlrev_b64 v[0:1], 13, v[0:1]
	s_mov_b32 s12, 0x80000
	v_lshl_add_u64 v[0:1], s[6:7], 0, v[0:1]
	v_add_co_u32_e32 v54, vcc, s12, v14
	v_lshl_add_u64 v[0:1], v[0:1], 0, v[152:153]
	s_nop 0
	v_addc_co_u32_e32 v55, vcc, 0, v15, vcc
	s_lshl_b32 s13, s19, 13
	s_lshl_b32 s21, s20, 8
	s_and_b32 s22, s18, 7
	v_lshrrev_b32_e32 v6, 2, v8
	v_add_co_u32_e32 v2, vcc, s12, v0
	s_and_b32 s13, s13, 0x600000
	s_and_b32 s21, s21, 0x6000
	s_lshl_b32 s24, s22, 10
	v_and_b32_e32 v6, 12, v6
	s_movk_i32 s22, 0x1230
	v_addc_co_u32_e32 v3, vcc, 0, v1, vcc
	s_mov_b32 s12, 0x100000
	v_lshrrev_b32_e64 v10, v6, s22
	s_add_u32 s22, s15, s13
	v_add_co_u32_e32 v4, vcc, s12, v0
	s_addc_u32 s23, s16, 0
	s_or_b32 s13, s24, s21
	v_addc_co_u32_e32 v5, vcc, 0, v1, vcc
	s_mov_b32 s12, 0x180000
	v_and_b32_e32 v22, 3, v8
	v_ashrrev_i32_e32 v13, 31, v12
	v_xor_b32_e32 v8, v10, v8
	s_or_b32 s13, s13, s65
	v_add_co_u32_e32 v20, vcc, s12, v0
	v_lshlrev_b32_e32 v9, 6, v12
	v_lshlrev_b64 v[6:7], 13, v[12:13]
	v_lshlrev_b32_e32 v8, 4, v8
	v_add_u32_e32 v12, s13, v12
	v_addc_co_u32_e32 v21, vcc, 0, v1, vcc
	s_nop 0
	v_readfirstlane_b32 s26, v14
	v_readfirstlane_b32 s27, v15
	v_readfirstlane_b32 s28, v0
	v_readfirstlane_b32 s29, v1
	v_lshrrev_b32_e32 v250, 6, v198
	s_nop 0
	v_readfirstlane_b32 s24, v250
	s_lshl_b32 s24, s24, 10
	v_lshrrev_b32_e32 v250, 2, v200
	v_lshrrev_b32_e32 v251, 4, v200
	v_lshlrev_b32_e32 v251, 2, v251
	v_mov_b32_e32 v248, 0x1230
	v_lshrrev_b32_e32 v251, v251, v248
	v_xor_b32_e32 v251, v251, v200
	v_and_b32_e32 v251, 3, v251
	v_lshlrev_b32_e32 v251, 4, v251
	v_lshl_add_u32 v244, v250, 13, v251
	v_add_u32_e32 v245, 0x80000, v244
	v_add_u32_e32 v246, 0x100000, v244
	v_add_u32_e32 v247, 0x180000, v244
	s_mov_b32 s25, 0
	s_add_u32 m0, s25, s24
	s_nop 0
	global_load_lds_dwordx4 v244, s[26:27]
	s_add_u32 m0, m0, 0x1000
	s_nop 0
	global_load_lds_dwordx4 v245, s[26:27]
	s_add_u32 m0, m0, 0x1000
	s_nop 0
	global_load_lds_dwordx4 v244, s[28:29]
	s_add_u32 m0, m0, 0x1000
	s_nop 0
	global_load_lds_dwordx4 v245, s[28:29]
	s_add_u32 m0, m0, 0x1000
	s_nop 0
	global_load_lds_dwordx4 v246, s[28:29]
	s_add_u32 m0, m0, 0x1000
	s_nop 0
	global_load_lds_dwordx4 v247, s[28:29]
	s_add_u32 s26, s26, 64
	s_addc_u32 s27, s27, 0
	s_add_u32 s28, s28, 64
	s_addc_u32 s29, s29, 0
	s_add_u32 s25, s25, 24576
	s_cmp_eq_u32 s25, 73728
	s_cselect_b32 s25, 0, s25
	s_add_u32 m0, s25, s24
	s_nop 0
	global_load_lds_dwordx4 v244, s[26:27]
	s_add_u32 m0, m0, 0x1000
	s_nop 0
	global_load_lds_dwordx4 v245, s[26:27]
	s_add_u32 m0, m0, 0x1000
	s_nop 0
	global_load_lds_dwordx4 v244, s[28:29]
	s_add_u32 m0, m0, 0x1000
	s_nop 0
	global_load_lds_dwordx4 v245, s[28:29]
	s_add_u32 m0, m0, 0x1000
	s_nop 0
	global_load_lds_dwordx4 v246, s[28:29]
	s_add_u32 m0, m0, 0x1000
	s_nop 0
	global_load_lds_dwordx4 v247, s[28:29]
	s_add_u32 s26, s26, 64
	s_addc_u32 s27, s27, 0
	s_add_u32 s28, s28, 64
	s_addc_u32 s29, s29, 0
	s_add_u32 s25, s25, 24576
	s_cmp_eq_u32 s25, 73728
	s_cselect_b32 s25, 0, s25
	s_add_u32 m0, s25, s24
	s_nop 0
	global_load_lds_dwordx4 v244, s[26:27]
	s_add_u32 m0, m0, 0x1000
	s_nop 0
	global_load_lds_dwordx4 v245, s[26:27]
	s_add_u32 m0, m0, 0x1000
	s_nop 0
	global_load_lds_dwordx4 v244, s[28:29]
	s_add_u32 m0, m0, 0x1000
	s_nop 0
	global_load_lds_dwordx4 v245, s[28:29]
	s_add_u32 m0, m0, 0x1000
	s_nop 0
	global_load_lds_dwordx4 v246, s[28:29]
	s_add_u32 m0, m0, 0x1000
	s_nop 0
	global_load_lds_dwordx4 v247, s[28:29]
	s_add_u32 s26, s26, 64
	s_addc_u32 s27, s27, 0
	s_add_u32 s28, s28, 64
	s_addc_u32 s29, s29, 0
	s_add_u32 s25, s25, 24576
	s_cmp_eq_u32 s25, 73728
	s_cselect_b32 s25, 0, s25
	v_mov_b32_e32 v24, 0
	v_mov_b32_e32 v25, v24
	v_mov_b32_e32 v26, v24
	v_mov_b32_e32 v27, v24
	v_mov_b32_e32 v28, v24
	v_mov_b32_e32 v29, v24
	v_mov_b32_e32 v54, v24
	v_mov_b32_e32 v55, v24
	v_mov_b32_e32 v56, v24
	v_mov_b32_e32 v57, v24
	v_mov_b32_e32 v58, v24
	v_mov_b32_e32 v59, v24
	v_mov_b32_e32 v64, v24
	v_mov_b32_e32 v65, v24
	v_mov_b32_e32 v66, v24
	v_mov_b32_e32 v67, v24
	v_mov_b32_e32 v68, v24
	v_mov_b32_e32 v69, v24
	v_mov_b32_e32 v70, v24
	v_mov_b32_e32 v71, v24
	v_mov_b32_e32 v60, v24
	v_mov_b32_e32 v61, v24
	v_mov_b32_e32 v62, v24
	v_mov_b32_e32 v63, v24
	v_mov_b32_e32 v100, v24
	v_mov_b32_e32 v30, v24
	v_mov_b32_e32 v31, v24
	v_mov_b32_e32 v32, v24
	v_mov_b32_e32 v33, v24
	v_mov_b32_e32 v34, v24
	v_mov_b32_e32 v35, v24
	v_mov_b32_e32 v36, v24
	v_mov_b32_e32 v37, v24
	v_mov_b32_e32 v38, v24
	v_mov_b32_e32 v39, v24
	v_mov_b32_e32 v52, v24
	v_mov_b32_e32 v53, v24
	v_mov_b32_e32 v40, v24
	v_mov_b32_e32 v41, v24
	v_mov_b32_e32 v42, v24
	v_mov_b32_e32 v43, v24
	v_mov_b32_e32 v44, v24
	v_mov_b32_e32 v45, v24
	v_mov_b32_e32 v46, v24
	v_mov_b32_e32 v47, v24
	v_mov_b32_e32 v48, v24
	v_mov_b32_e32 v49, v24
	v_mov_b32_e32 v50, v24
	v_mov_b32_e32 v51, v24
	v_mov_b32_e32 v101, v24
	v_mov_b32_e32 v102, v24
	v_mov_b32_e32 v103, v24
	v_mov_b32_e32 v104, v24
	v_mov_b32_e32 v105, v24
	v_mov_b32_e32 v106, v24
	v_mov_b32_e32 v107, v24
	v_mov_b32_e32 v120, v24
	v_mov_b32_e32 v121, v24
	v_mov_b32_e32 v122, v24
	v_mov_b32_e32 v123, v24
	v_mov_b32_e32 v128, v24
	v_mov_b32_e32 v129, v24
	v_mov_b32_e32 v130, v24
	v_mov_b32_e32 v131, v24
	v_mov_b32_e32 v108, v24
	v_mov_b32_e32 v109, v24
	v_mov_b32_e32 v110, v24
	v_mov_b32_e32 v111, v24
	v_mov_b32_e32 v112, v24
	v_mov_b32_e32 v113, v24
	v_mov_b32_e32 v114, v24
	v_mov_b32_e32 v115, v24
	v_mov_b32_e32 v116, v24
	v_mov_b32_e32 v117, v24
	v_mov_b32_e32 v118, v24
	v_mov_b32_e32 v119, v24
	v_mov_b32_e32 v124, v24
	v_mov_b32_e32 v125, v24
	v_mov_b32_e32 v126, v24
	v_mov_b32_e32 v127, v24
	v_mov_b32_e32 v80, v24
	v_mov_b32_e32 v81, v24
	v_mov_b32_e32 v82, v24
	v_mov_b32_e32 v83, v24
	v_mov_b32_e32 v84, v24
	v_mov_b32_e32 v85, v24
	v_mov_b32_e32 v86, v24
	v_mov_b32_e32 v87, v24
	v_mov_b32_e32 v96, v24
	v_mov_b32_e32 v97, v24
	v_mov_b32_e32 v98, v24
	v_mov_b32_e32 v99, v24
	v_mov_b32_e32 v72, v24
	v_mov_b32_e32 v73, v24
	v_mov_b32_e32 v74, v24
	v_mov_b32_e32 v75, v24
	v_mov_b32_e32 v132, v24
	v_mov_b32_e32 v133, v24
	v_mov_b32_e32 v134, v24
	v_mov_b32_e32 v135, v24
	v_mov_b32_e32 v136, v24
	v_mov_b32_e32 v137, v24
	v_mov_b32_e32 v138, v24
	v_mov_b32_e32 v139, v24
	v_mov_b32_e32 v140, v24
	v_mov_b32_e32 v141, v24
	v_mov_b32_e32 v142, v24
	v_mov_b32_e32 v143, v24
	v_mov_b32_e32 v144, v24
	v_mov_b32_e32 v145, v24
	v_mov_b32_e32 v146, v24
	v_mov_b32_e32 v147, v24
	v_mov_b32_e32 v92, v24
	v_mov_b32_e32 v93, v24
	v_mov_b32_e32 v94, v24
	v_mov_b32_e32 v95, v24
	v_mov_b32_e32 v88, v24
	v_mov_b32_e32 v89, v24
	v_mov_b32_e32 v90, v24
	v_mov_b32_e32 v91, v24
	v_mov_b32_e32 v76, v24
	v_mov_b32_e32 v77, v24
	v_mov_b32_e32 v78, v24
	v_mov_b32_e32 v79, v24
	v_mov_b32_e32 v148, v24
	v_mov_b32_e32 v149, v24
	v_mov_b32_e32 v150, v24
	v_mov_b32_e32 v151, v24
	s_waitcnt vmcnt(12)
	s_barrier
	s_mov_b32 s30, 0
	v_add_u32_e32 v248, s30, v155
	v_add_u32_e32 v249, s30, v160
	ds_read_b128 v[186:189], v248
	ds_read_b128 v[212:215], v249 offset:8192
	ds_read_b128 v[190:193], v248 offset:1024
	ds_read_b128 v[216:219], v249 offset:9216
	ds_read_b128 v[194:197], v248 offset:2048
	ds_read_b128 v[220:223], v249 offset:10240
	ds_read_b128 v[208:211], v248 offset:3072
	ds_read_b128 v[224:227], v249 offset:11264
	ds_read_b128 v[228:231], v249 offset:12288
	ds_read_b128 v[232:235], v249 offset:13312
	ds_read_b128 v[236:239], v249 offset:14336
	ds_read_b128 v[240:243], v249 offset:15360
	s_add_u32 s30, s30, 24576
	s_cmp_eq_u32 s30, 73728
	s_cselect_b32 s30, 0, s30
	s_waitcnt vmcnt(6)
	s_waitcnt lgkmcnt(0)
	s_barrier
	s_mov_b32 s31, 62
	.p2alignl 6, 3212836864

.Lproj_cd:
	s_or_b32 s4, s16, s67
	v_mov_b32 v10, v198
	v_ashrrev_i32_e32 v0, 2, v10
	s_lshl_b32 s4, s4, 7
	v_add_u32_e32 v2, s4, v0
	v_ashrrev_i32_e32 v3, 31, v2
	v_lshlrev_b64 v[2:3], 11, v[2:3]
	v_lshlrev_b32_e32 v1, 4, v10
	v_add_u32_e32 v4, s17, v0
	v_lshl_add_u64 v[2:3], s[96:97], 0, v[2:3]
	v_and_b32_e32 v152, 48, v1
	v_ashrrev_i32_e32 v5, 31, v4
	v_lshl_add_u64 v[2:3], v[2:3], 0, v[152:153]
	v_lshlrev_b64 v[4:5], 11, v[4:5]
	v_lshl_add_u64 v[156:157], s[8:9], 0, v[4:5]
	v_add_co_u32_e32 v6, vcc, s62, v2
	v_lshl_add_u64 v[4:5], v[156:157], 0, v[152:153]
	s_nop 0
	v_addc_co_u32_e32 v7, vcc, 0, v3, vcc
	v_add_co_u32_e32 v8, vcc, s62, v4
	s_and_b32 s7, s42, 56
	v_lshrrev_b32_e32 v1, 2, v10
	s_or_b32 s6, s67, s6
	v_addc_co_u32_e32 v9, vcc, 0, v5, vcc
	v_and_b32_e32 v12, 12, v1
	s_movk_i32 s20, 0x1230
	s_or_b32 s84, s6, s7
	v_add_co_u32_e32 v60, vcc, s33, v4
	v_lshrrev_b32_e64 v12, v12, s20
	s_lshl_b64 s[6:7], s[84:85], 18
	v_addc_co_u32_e32 v61, vcc, 0, v5, vcc
	v_and_b32_e32 v11, 3, v10
	v_ashrrev_i32_e32 v1, 31, v0
	v_xor_b32_e32 v10, v12, v10
	s_add_u32 s6, s82, s6
	v_add_co_u32_e32 v62, vcc, s72, v4
	v_lshlrev_b32_e32 v13, 6, v0
	v_lshlrev_b64 v[0:1], 11, v[0:1]
	v_lshlrev_b32_e32 v10, 4, v10
	s_addc_u32 s7, s83, s7
	v_addc_co_u32_e32 v63, vcc, 0, v5, vcc
	s_nop 0
	v_readfirstlane_b32 s26, v2
	v_readfirstlane_b32 s27, v3
	v_readfirstlane_b32 s28, v4
	v_readfirstlane_b32 s29, v5
	v_lshrrev_b32_e32 v250, 6, v198
	s_nop 0
	v_readfirstlane_b32 s24, v250
	s_lshl_b32 s24, s24, 10
	v_lshrrev_b32_e32 v250, 2, v200
	v_lshrrev_b32_e32 v251, 4, v200
	v_lshlrev_b32_e32 v251, 2, v251
	v_mov_b32_e32 v248, 0x1230
	v_lshrrev_b32_e32 v251, v251, v248
	v_xor_b32_e32 v251, v251, v200
	v_and_b32_e32 v251, 3, v251
	v_lshlrev_b32_e32 v251, 4, v251
	v_lshl_add_u32 v244, v250, 11, v251
	v_add_u32_e32 v245, 0x20000, v244
	v_add_u32_e32 v246, 0x40000, v244
	v_add_u32_e32 v247, 0x60000, v244
	s_mov_b32 s25, 0
	s_add_u32 m0, s25, s24
	s_nop 0
	global_load_lds_dwordx4 v244, s[26:27]
	s_add_u32 m0, m0, 0x1000
	s_nop 0
	global_load_lds_dwordx4 v245, s[26:27]
	s_add_u32 m0, m0, 0x1000
	s_nop 0
	global_load_lds_dwordx4 v244, s[28:29]
	s_add_u32 m0, m0, 0x1000
	s_nop 0
	global_load_lds_dwordx4 v245, s[28:29]
	s_add_u32 m0, m0, 0x1000
	s_nop 0
	global_load_lds_dwordx4 v246, s[28:29]
	s_add_u32 m0, m0, 0x1000
	s_nop 0
	global_load_lds_dwordx4 v247, s[28:29]
	s_add_u32 s26, s26, 64
	s_addc_u32 s27, s27, 0
	s_add_u32 s28, s28, 64
	s_addc_u32 s29, s29, 0
	s_add_u32 s25, s25, 24576
	s_cmp_eq_u32 s25, 73728
	s_cselect_b32 s25, 0, s25
	s_add_u32 m0, s25, s24
	s_nop 0
	global_load_lds_dwordx4 v244, s[26:27]
	s_add_u32 m0, m0, 0x1000
	s_nop 0
	global_load_lds_dwordx4 v245, s[26:27]
	s_add_u32 m0, m0, 0x1000
	s_nop 0
	global_load_lds_dwordx4 v244, s[28:29]
	s_add_u32 m0, m0, 0x1000
	s_nop 0
	global_load_lds_dwordx4 v245, s[28:29]
	s_add_u32 m0, m0, 0x1000
	s_nop 0
	global_load_lds_dwordx4 v246, s[28:29]
	s_add_u32 m0, m0, 0x1000
	s_nop 0
	global_load_lds_dwordx4 v247, s[28:29]
	s_add_u32 s26, s26, 64
	s_addc_u32 s27, s27, 0
	s_add_u32 s28, s28, 64
	s_addc_u32 s29, s29, 0
	s_add_u32 s25, s25, 24576
	s_cmp_eq_u32 s25, 73728
	s_cselect_b32 s25, 0, s25
	s_add_u32 m0, s25, s24
	s_nop 0
	global_load_lds_dwordx4 v244, s[26:27]
	s_add_u32 m0, m0, 0x1000
	s_nop 0
	global_load_lds_dwordx4 v245, s[26:27]
	s_add_u32 m0, m0, 0x1000
	s_nop 0
	global_load_lds_dwordx4 v244, s[28:29]
	s_add_u32 m0, m0, 0x1000
	s_nop 0
	global_load_lds_dwordx4 v245, s[28:29]
	s_add_u32 m0, m0, 0x1000
	s_nop 0
	global_load_lds_dwordx4 v246, s[28:29]
	s_add_u32 m0, m0, 0x1000
	s_nop 0
	global_load_lds_dwordx4 v247, s[28:29]
	s_add_u32 s26, s26, 64
	s_addc_u32 s27, s27, 0
	s_add_u32 s28, s28, 64
	s_addc_u32 s29, s29, 0
	s_add_u32 s25, s25, 24576
	s_cmp_eq_u32 s25, 73728
	s_cselect_b32 s25, 0, s25
	v_mov_b32_e32 v24, 0
	v_mov_b32_e32 v25, v24
	v_mov_b32_e32 v26, v24
	v_mov_b32_e32 v27, v24
	v_mov_b32_e32 v28, v24
	v_mov_b32_e32 v29, v24
	v_mov_b32_e32 v30, v24
	v_mov_b32_e32 v31, v24
	v_mov_b32_e32 v32, v24
	v_mov_b32_e32 v33, v24
	v_mov_b32_e32 v34, v24
	v_mov_b32_e32 v35, v24
	v_mov_b32_e32 v64, v24
	v_mov_b32_e32 v65, v24
	v_mov_b32_e32 v66, v24
	v_mov_b32_e32 v67, v24
	v_mov_b32_e32 v68, v24
	v_mov_b32_e32 v69, v24
	v_mov_b32_e32 v70, v24
	v_mov_b32_e32 v71, v24
	v_mov_b32_e32 v60, v24
	v_mov_b32_e32 v61, v24
	v_mov_b32_e32 v62, v24
	v_mov_b32_e32 v63, v24
	v_mov_b32_e32 v100, v24
	v_mov_b32_e32 v101, v24
	v_mov_b32_e32 v102, v24
	v_mov_b32_e32 v103, v24
	v_mov_b32_e32 v104, v24
	v_mov_b32_e32 v105, v24
	v_mov_b32_e32 v106, v24
	v_mov_b32_e32 v107, v24
	v_mov_b32_e32 v120, v24
	v_mov_b32_e32 v121, v24
	v_mov_b32_e32 v122, v24
	v_mov_b32_e32 v36, v24
	v_mov_b32_e32 v37, v24
	v_mov_b32_e32 v38, v24
	v_mov_b32_e32 v39, v24
	v_mov_b32_e32 v52, v24
	v_mov_b32_e32 v53, v24
	v_mov_b32_e32 v54, v24
	v_mov_b32_e32 v55, v24
	v_mov_b32_e32 v56, v24
	v_mov_b32_e32 v57, v24
	v_mov_b32_e32 v58, v24
	v_mov_b32_e32 v59, v24
	v_mov_b32_e32 v40, v24
	v_mov_b32_e32 v41, v24
	v_mov_b32_e32 v42, v24
	v_mov_b32_e32 v43, v24
	v_mov_b32_e32 v44, v24
	v_mov_b32_e32 v45, v24
	v_mov_b32_e32 v46, v24
	v_mov_b32_e32 v47, v24
	v_mov_b32_e32 v48, v24
	v_mov_b32_e32 v49, v24
	v_mov_b32_e32 v50, v24
	v_mov_b32_e32 v51, v24
	v_mov_b32_e32 v123, v24
	v_mov_b32_e32 v128, v24
	v_mov_b32_e32 v129, v24
	v_mov_b32_e32 v130, v24
	v_mov_b32_e32 v131, v24
	v_mov_b32_e32 v108, v24
	v_mov_b32_e32 v109, v24
	v_mov_b32_e32 v110, v24
	v_mov_b32_e32 v111, v24
	v_mov_b32_e32 v112, v24
	v_mov_b32_e32 v113, v24
	v_mov_b32_e32 v114, v24
	v_mov_b32_e32 v115, v24
	v_mov_b32_e32 v116, v24
	v_mov_b32_e32 v117, v24
	v_mov_b32_e32 v118, v24
	v_mov_b32_e32 v119, v24
	v_mov_b32_e32 v124, v24
	v_mov_b32_e32 v125, v24
	v_mov_b32_e32 v126, v24
	v_mov_b32_e32 v127, v24
	v_mov_b32_e32 v80, v24
	v_mov_b32_e32 v81, v24
	v_mov_b32_e32 v82, v24
	v_mov_b32_e32 v83, v24
	v_mov_b32_e32 v88, v24
	v_mov_b32_e32 v89, v24
	v_mov_b32_e32 v90, v24
	v_mov_b32_e32 v91, v24
	v_mov_b32_e32 v92, v24
	v_mov_b32_e32 v93, v24
	v_mov_b32_e32 v94, v24
	v_mov_b32_e32 v95, v24
	v_mov_b32_e32 v76, v24
	v_mov_b32_e32 v77, v24
	v_mov_b32_e32 v78, v24
	v_mov_b32_e32 v79, v24
	v_mov_b32_e32 v132, v24
	v_mov_b32_e32 v133, v24
	v_mov_b32_e32 v134, v24
	v_mov_b32_e32 v135, v24
	v_mov_b32_e32 v136, v24
	v_mov_b32_e32 v137, v24
	v_mov_b32_e32 v138, v24
	v_mov_b32_e32 v139, v24
	v_mov_b32_e32 v140, v24
	v_mov_b32_e32 v141, v24
	v_mov_b32_e32 v142, v24
	v_mov_b32_e32 v143, v24
	v_mov_b32_e32 v144, v24
	v_mov_b32_e32 v145, v24
	v_mov_b32_e32 v146, v24
	v_mov_b32_e32 v147, v24
	v_mov_b32_e32 v96, v24
	v_mov_b32_e32 v97, v24
	v_mov_b32_e32 v98, v24
	v_mov_b32_e32 v99, v24
	v_mov_b32_e32 v84, v24
	v_mov_b32_e32 v85, v24
	v_mov_b32_e32 v86, v24
	v_mov_b32_e32 v87, v24
	v_mov_b32_e32 v72, v24
	v_mov_b32_e32 v73, v24
	v_mov_b32_e32 v74, v24
	v_mov_b32_e32 v75, v24
	v_mov_b32_e32 v148, v24
	v_mov_b32_e32 v149, v24
	v_mov_b32_e32 v150, v24
	v_mov_b32_e32 v151, v24
	s_waitcnt vmcnt(12)
	s_barrier
	s_mov_b32 s30, 0
	v_add_u32_e32 v248, s30, v155
	v_add_u32_e32 v249, s30, v160
	ds_read_b128 v[186:189], v248
	ds_read_b128 v[212:215], v249 offset:8192
	ds_read_b128 v[190:193], v248 offset:1024
	ds_read_b128 v[216:219], v249 offset:9216
	ds_read_b128 v[194:197], v248 offset:2048
	ds_read_b128 v[220:223], v249 offset:10240
	ds_read_b128 v[208:211], v248 offset:3072
	ds_read_b128 v[224:227], v249 offset:11264
	ds_read_b128 v[228:231], v249 offset:12288
	ds_read_b128 v[232:235], v249 offset:13312
	ds_read_b128 v[236:239], v249 offset:14336
	ds_read_b128 v[240:243], v249 offset:15360
	s_add_u32 s30, s30, 24576
	s_cmp_eq_u32 s30, 73728
	s_cselect_b32 s30, 0, s30
	s_waitcnt vmcnt(6)
	s_waitcnt lgkmcnt(0)
	s_barrier
	s_mov_b32 s31, 14
	s_cmpk_lt_u32 s43, 0x180
	s_cbranch_scc0 .Lgm3_cheap
	.p2alignl 6, 3212836864
.Lgm3_loop:
	v_add_u32_e32 v248, s30, v155
	v_add_u32_e32 v249, s30, v160
	v_mfma_f32_16x16x32_bf16 v[128:131], v[212:215], v[186:189], v[128:131]
	ds_read_b128 v[0:3], v248
	v_mfma_f32_16x16x32_bf16 v[68:71], v[212:215], v[190:193], v[68:71]
	ds_read_b128 v[16:19], v249 offset:8192
	v_mfma_f32_16x16x32_bf16 v[108:111], v[212:215], v[194:197], v[108:111]
	ds_read_b128 v[4:7], v248 offset:1024
	v_mfma_f32_16x16x32_bf16 v[132:135], v[212:215], v[208:211], v[132:135]
	ds_read_b128 v[20:23], v249 offset:9216
	v_mfma_f32_16x16x32_bf16 v[120:123], v[216:219], v[186:189], v[120:123]
	ds_read_b128 v[8:11], v248 offset:2048
	v_mfma_f32_16x16x32_bf16 v[64:67], v[216:219], v[190:193], v[64:67]
	ds_read_b128 v[162:165], v249 offset:10240
	v_mfma_f32_16x16x32_bf16 v[112:115], v[216:219], v[194:197], v[112:115]
	ds_read_b128 v[12:15], v248 offset:3072
	v_mfma_f32_16x16x32_bf16 v[136:139], v[216:219], v[208:211], v[136:139]
	ds_read_b128 v[166:169], v249 offset:11264
	v_mfma_f32_16x16x32_bf16 v[104:107], v[220:223], v[186:189], v[104:107]
	ds_read_b128 v[170:173], v249 offset:12288
	v_mfma_f32_16x16x32_bf16 v[56:59], v[220:223], v[190:193], v[56:59]
	ds_read_b128 v[174:177], v249 offset:13312
	v_mfma_f32_16x16x32_bf16 v[116:119], v[220:223], v[194:197], v[116:119]
	ds_read_b128 v[178:181], v249 offset:14336
	v_mfma_f32_16x16x32_bf16 v[140:143], v[220:223], v[208:211], v[140:143]
	ds_read_b128 v[182:185], v249 offset:15360
	s_add_u32 m0, s25, s24
	v_mfma_f32_16x16x32_bf16 v[100:103], v[224:227], v[186:189], v[100:103]
	global_load_lds_dwordx4 v244, s[26:27]
	v_mfma_f32_16x16x32_bf16 v[52:55], v[224:227], v[190:193], v[52:55]
	v_mfma_f32_16x16x32_bf16 v[124:127], v[224:227], v[194:197], v[124:127]
	s_add_u32 m0, m0, 0x1000
	v_mfma_f32_16x16x32_bf16 v[144:147], v[224:227], v[208:211], v[144:147]
	global_load_lds_dwordx4 v245, s[26:27]
	v_mfma_f32_16x16x32_bf16 v[60:63], v[228:231], v[186:189], v[60:63]
	v_mfma_f32_16x16x32_bf16 v[36:39], v[228:231], v[190:193], v[36:39]
	s_add_u32 m0, m0, 0x1000
	v_mfma_f32_16x16x32_bf16 v[80:83], v[228:231], v[194:197], v[80:83]
	global_load_lds_dwordx4 v244, s[28:29]
	v_mfma_f32_16x16x32_bf16 v[96:99], v[228:231], v[208:211], v[96:99]
	v_mfma_f32_16x16x32_bf16 v[48:51], v[232:235], v[186:189], v[48:51]
	s_add_u32 m0, m0, 0x1000
	v_mfma_f32_16x16x32_bf16 v[32:35], v[232:235], v[190:193], v[32:35]
	global_load_lds_dwordx4 v245, s[28:29]
	v_mfma_f32_16x16x32_bf16 v[88:91], v[232:235], v[194:197], v[88:91]
	v_mfma_f32_16x16x32_bf16 v[84:87], v[232:235], v[208:211], v[84:87]
	s_add_u32 m0, m0, 0x1000
	v_mfma_f32_16x16x32_bf16 v[44:47], v[236:239], v[186:189], v[44:47]
	global_load_lds_dwordx4 v246, s[28:29]
	v_mfma_f32_16x16x32_bf16 v[28:31], v[236:239], v[190:193], v[28:31]
	v_mfma_f32_16x16x32_bf16 v[92:95], v[236:239], v[194:197], v[92:95]
	s_add_u32 m0, m0, 0x1000
	v_mfma_f32_16x16x32_bf16 v[72:75], v[236:239], v[208:211], v[72:75]
	global_load_lds_dwordx4 v247, s[28:29]
	v_mfma_f32_16x16x32_bf16 v[40:43], v[240:243], v[186:189], v[40:43]
	v_mfma_f32_16x16x32_bf16 v[24:27], v[240:243], v[190:193], v[24:27]
	v_mfma_f32_16x16x32_bf16 v[76:79], v[240:243], v[194:197], v[76:79]
	v_mfma_f32_16x16x32_bf16 v[148:151], v[240:243], v[208:211], v[148:151]
	s_add_u32 s26, s26, 64
	s_addc_u32 s27, s27, 0
	s_add_u32 s28, s28, 64
	s_addc_u32 s29, s29, 0
	s_add_u32 s25, s25, 24576
	s_cmp_eq_u32 s25, 73728
	s_cselect_b32 s25, 0, s25
	s_add_u32 s30, s30, 24576
	s_cmp_eq_u32 s30, 73728
	s_cselect_b32 s30, 0, s30
	s_waitcnt vmcnt(6)
	s_waitcnt lgkmcnt(0)
	s_barrier
	v_add_u32_e32 v248, s30, v155
	v_add_u32_e32 v249, s30, v160
	v_mfma_f32_16x16x32_bf16 v[128:131], v[16:19], v[0:3], v[128:131]
	ds_read_b128 v[186:189], v248
	v_mfma_f32_16x16x32_bf16 v[68:71], v[16:19], v[4:7], v[68:71]
	ds_read_b128 v[212:215], v249 offset:8192
	v_mfma_f32_16x16x32_bf16 v[108:111], v[16:19], v[8:11], v[108:111]
	ds_read_b128 v[190:193], v248 offset:1024
	v_mfma_f32_16x16x32_bf16 v[132:135], v[16:19], v[12:15], v[132:135]
	ds_read_b128 v[216:219], v249 offset:9216
	v_mfma_f32_16x16x32_bf16 v[120:123], v[20:23], v[0:3], v[120:123]
	ds_read_b128 v[194:197], v248 offset:2048
	v_mfma_f32_16x16x32_bf16 v[64:67], v[20:23], v[4:7], v[64:67]
	ds_read_b128 v[220:223], v249 offset:10240
	v_mfma_f32_16x16x32_bf16 v[112:115], v[20:23], v[8:11], v[112:115]
	ds_read_b128 v[208:211], v248 offset:3072
	v_mfma_f32_16x16x32_bf16 v[136:139], v[20:23], v[12:15], v[136:139]
	ds_read_b128 v[224:227], v249 offset:11264
	v_mfma_f32_16x16x32_bf16 v[104:107], v[162:165], v[0:3], v[104:107]
	ds_read_b128 v[228:231], v249 offset:12288
	v_mfma_f32_16x16x32_bf16 v[56:59], v[162:165], v[4:7], v[56:59]
	ds_read_b128 v[232:235], v249 offset:13312
	v_mfma_f32_16x16x32_bf16 v[116:119], v[162:165], v[8:11], v[116:119]
	ds_read_b128 v[236:239], v249 offset:14336
	v_mfma_f32_16x16x32_bf16 v[140:143], v[162:165], v[12:15], v[140:143]
	ds_read_b128 v[240:243], v249 offset:15360
	s_add_u32 m0, s25, s24
	v_mfma_f32_16x16x32_bf16 v[100:103], v[166:169], v[0:3], v[100:103]
	global_load_lds_dwordx4 v244, s[26:27]
	v_mfma_f32_16x16x32_bf16 v[52:55], v[166:169], v[4:7], v[52:55]
	v_mfma_f32_16x16x32_bf16 v[124:127], v[166:169], v[8:11], v[124:127]
	s_add_u32 m0, m0, 0x1000
	v_mfma_f32_16x16x32_bf16 v[144:147], v[166:169], v[12:15], v[144:147]
	global_load_lds_dwordx4 v245, s[26:27]
	v_mfma_f32_16x16x32_bf16 v[60:63], v[170:173], v[0:3], v[60:63]
	v_mfma_f32_16x16x32_bf16 v[36:39], v[170:173], v[4:7], v[36:39]
	s_add_u32 m0, m0, 0x1000
	v_mfma_f32_16x16x32_bf16 v[80:83], v[170:173], v[8:11], v[80:83]
	global_load_lds_dwordx4 v244, s[28:29]
	v_mfma_f32_16x16x32_bf16 v[96:99], v[170:173], v[12:15], v[96:99]
	v_mfma_f32_16x16x32_bf16 v[48:51], v[174:177], v[0:3], v[48:51]
	s_add_u32 m0, m0, 0x1000
	v_mfma_f32_16x16x32_bf16 v[32:35], v[174:177], v[4:7], v[32:35]
	global_load_lds_dwordx4 v245, s[28:29]
	v_mfma_f32_16x16x32_bf16 v[88:91], v[174:177], v[8:11], v[88:91]
	v_mfma_f32_16x16x32_bf16 v[84:87], v[174:177], v[12:15], v[84:87]
	s_add_u32 m0, m0, 0x1000
	v_mfma_f32_16x16x32_bf16 v[44:47], v[178:181], v[0:3], v[44:47]
	global_load_lds_dwordx4 v246, s[28:29]
	v_mfma_f32_16x16x32_bf16 v[28:31], v[178:181], v[4:7], v[28:31]
	v_mfma_f32_16x16x32_bf16 v[92:95], v[178:181], v[8:11], v[92:95]
	s_add_u32 m0, m0, 0x1000
	v_mfma_f32_16x16x32_bf16 v[72:75], v[178:181], v[12:15], v[72:75]
	global_load_lds_dwordx4 v247, s[28:29]
	v_mfma_f32_16x16x32_bf16 v[40:43], v[182:185], v[0:3], v[40:43]
	v_mfma_f32_16x16x32_bf16 v[24:27], v[182:185], v[4:7], v[24:27]
	v_mfma_f32_16x16x32_bf16 v[76:79], v[182:185], v[8:11], v[76:79]
	v_mfma_f32_16x16x32_bf16 v[148:151], v[182:185], v[12:15], v[148:151]
	s_add_u32 s26, s26, 64
	s_addc_u32 s27, s27, 0
	s_add_u32 s28, s28, 64
	s_addc_u32 s29, s29, 0
	s_add_u32 s25, s25, 24576
	s_cmp_eq_u32 s25, 73728
	s_cselect_b32 s25, 0, s25
	s_add_u32 s30, s30, 24576
	s_cmp_eq_u32 s30, 73728
	s_cselect_b32 s30, 0, s30
	s_waitcnt vmcnt(6)
	s_waitcnt lgkmcnt(0)
	s_barrier
	s_sub_u32 s31, s31, 1
	s_cmp_lg_u32 s31, 0
	s_cbranch_scc1 .Lgm3_loop
	v_add_u32_e32 v248, s30, v155
	v_add_u32_e32 v249, s30, v160
	v_mfma_f32_16x16x32_bf16 v[128:131], v[212:215], v[186:189], v[128:131]
	ds_read_b128 v[0:3], v248
	v_mfma_f32_16x16x32_bf16 v[68:71], v[212:215], v[190:193], v[68:71]
	ds_read_b128 v[16:19], v249 offset:8192
	v_mfma_f32_16x16x32_bf16 v[108:111], v[212:215], v[194:197], v[108:111]
	ds_read_b128 v[4:7], v248 offset:1024
	v_mfma_f32_16x16x32_bf16 v[132:135], v[212:215], v[208:211], v[132:135]
	ds_read_b128 v[20:23], v249 offset:9216
	v_mfma_f32_16x16x32_bf16 v[120:123], v[216:219], v[186:189], v[120:123]
	ds_read_b128 v[8:11], v248 offset:2048
	v_mfma_f32_16x16x32_bf16 v[64:67], v[216:219], v[190:193], v[64:67]
	ds_read_b128 v[162:165], v249 offset:10240
	v_mfma_f32_16x16x32_bf16 v[112:115], v[216:219], v[194:197], v[112:115]
	ds_read_b128 v[12:15], v248 offset:3072
	v_mfma_f32_16x16x32_bf16 v[136:139], v[216:219], v[208:211], v[136:139]
	ds_read_b128 v[166:169], v249 offset:11264
	v_mfma_f32_16x16x32_bf16 v[104:107], v[220:223], v[186:189], v[104:107]
	ds_read_b128 v[170:173], v249 offset:12288
	v_mfma_f32_16x16x32_bf16 v[56:59], v[220:223], v[190:193], v[56:59]
	ds_read_b128 v[174:177], v249 offset:13312
	v_mfma_f32_16x16x32_bf16 v[116:119], v[220:223], v[194:197], v[116:119]
	ds_read_b128 v[178:181], v249 offset:14336
	v_mfma_f32_16x16x32_bf16 v[140:143], v[220:223], v[208:211], v[140:143]
	ds_read_b128 v[182:185], v249 offset:15360
	s_add_u32 m0, s25, s24
	v_mfma_f32_16x16x32_bf16 v[100:103], v[224:227], v[186:189], v[100:103]
	global_load_lds_dwordx4 v244, s[26:27]
	v_mfma_f32_16x16x32_bf16 v[52:55], v[224:227], v[190:193], v[52:55]
	v_mfma_f32_16x16x32_bf16 v[124:127], v[224:227], v[194:197], v[124:127]
	s_add_u32 m0, m0, 0x1000
	v_mfma_f32_16x16x32_bf16 v[144:147], v[224:227], v[208:211], v[144:147]
	global_load_lds_dwordx4 v245, s[26:27]
	v_mfma_f32_16x16x32_bf16 v[60:63], v[228:231], v[186:189], v[60:63]
	v_mfma_f32_16x16x32_bf16 v[36:39], v[228:231], v[190:193], v[36:39]
	s_add_u32 m0, m0, 0x1000
	v_mfma_f32_16x16x32_bf16 v[80:83], v[228:231], v[194:197], v[80:83]
	global_load_lds_dwordx4 v244, s[28:29]
	v_mfma_f32_16x16x32_bf16 v[96:99], v[228:231], v[208:211], v[96:99]
	v_mfma_f32_16x16x32_bf16 v[48:51], v[232:235], v[186:189], v[48:51]
	s_add_u32 m0, m0, 0x1000
	v_mfma_f32_16x16x32_bf16 v[32:35], v[232:235], v[190:193], v[32:35]
	global_load_lds_dwordx4 v245, s[28:29]
	v_mfma_f32_16x16x32_bf16 v[88:91], v[232:235], v[194:197], v[88:91]
	v_mfma_f32_16x16x32_bf16 v[84:87], v[232:235], v[208:211], v[84:87]
	s_add_u32 m0, m0, 0x1000
	v_mfma_f32_16x16x32_bf16 v[44:47], v[236:239], v[186:189], v[44:47]
	global_load_lds_dwordx4 v246, s[28:29]
	v_mfma_f32_16x16x32_bf16 v[28:31], v[236:239], v[190:193], v[28:31]
	v_mfma_f32_16x16x32_bf16 v[92:95], v[236:239], v[194:197], v[92:95]
	s_add_u32 m0, m0, 0x1000
	v_mfma_f32_16x16x32_bf16 v[72:75], v[236:239], v[208:211], v[72:75]
	global_load_lds_dwordx4 v247, s[28:29]
	v_mfma_f32_16x16x32_bf16 v[40:43], v[240:243], v[186:189], v[40:43]
	v_mfma_f32_16x16x32_bf16 v[24:27], v[240:243], v[190:193], v[24:27]
	v_mfma_f32_16x16x32_bf16 v[76:79], v[240:243], v[194:197], v[76:79]
	v_mfma_f32_16x16x32_bf16 v[148:151], v[240:243], v[208:211], v[148:151]
	s_add_u32 s26, s26, 64
	s_addc_u32 s27, s27, 0
	s_add_u32 s28, s28, 64
	s_addc_u32 s29, s29, 0
	s_add_u32 s25, s25, 24576
	s_cmp_eq_u32 s25, 73728
	s_cselect_b32 s25, 0, s25
	s_add_u32 s30, s30, 24576
	s_cmp_eq_u32 s30, 73728
	s_cselect_b32 s30, 0, s30
	s_waitcnt vmcnt(6)
	s_waitcnt lgkmcnt(0)
	s_barrier
	v_mfma_f32_16x16x32_bf16 v[128:131], v[16:19], v[0:3], v[128:131]
	v_mfma_f32_16x16x32_bf16 v[68:71], v[16:19], v[4:7], v[68:71]
	v_mfma_f32_16x16x32_bf16 v[108:111], v[16:19], v[8:11], v[108:111]
	v_mfma_f32_16x16x32_bf16 v[132:135], v[16:19], v[12:15], v[132:135]
	v_mfma_f32_16x16x32_bf16 v[120:123], v[20:23], v[0:3], v[120:123]
	v_mfma_f32_16x16x32_bf16 v[64:67], v[20:23], v[4:7], v[64:67]
	v_mfma_f32_16x16x32_bf16 v[112:115], v[20:23], v[8:11], v[112:115]
	v_mfma_f32_16x16x32_bf16 v[136:139], v[20:23], v[12:15], v[136:139]
	v_mfma_f32_16x16x32_bf16 v[104:107], v[162:165], v[0:3], v[104:107]
	v_mfma_f32_16x16x32_bf16 v[56:59], v[162:165], v[4:7], v[56:59]
	v_mfma_f32_16x16x32_bf16 v[116:119], v[162:165], v[8:11], v[116:119]
	v_mfma_f32_16x16x32_bf16 v[140:143], v[162:165], v[12:15], v[140:143]
	v_mfma_f32_16x16x32_bf16 v[100:103], v[166:169], v[0:3], v[100:103]
	v_mfma_f32_16x16x32_bf16 v[52:55], v[166:169], v[4:7], v[52:55]
	v_mfma_f32_16x16x32_bf16 v[124:127], v[166:169], v[8:11], v[124:127]
	v_mfma_f32_16x16x32_bf16 v[144:147], v[166:169], v[12:15], v[144:147]
	v_mfma_f32_16x16x32_bf16 v[60:63], v[170:173], v[0:3], v[60:63]
	v_mfma_f32_16x16x32_bf16 v[36:39], v[170:173], v[4:7], v[36:39]
	v_mfma_f32_16x16x32_bf16 v[80:83], v[170:173], v[8:11], v[80:83]
	v_mfma_f32_16x16x32_bf16 v[96:99], v[170:173], v[12:15], v[96:99]
	v_mfma_f32_16x16x32_bf16 v[48:51], v[174:177], v[0:3], v[48:51]
	v_mfma_f32_16x16x32_bf16 v[32:35], v[174:177], v[4:7], v[32:35]
	v_mfma_f32_16x16x32_bf16 v[88:91], v[174:177], v[8:11], v[88:91]
	v_mfma_f32_16x16x32_bf16 v[84:87], v[174:177], v[12:15], v[84:87]
	v_mfma_f32_16x16x32_bf16 v[44:47], v[178:181], v[0:3], v[44:47]
	v_mfma_f32_16x16x32_bf16 v[28:31], v[178:181], v[4:7], v[28:31]
	v_mfma_f32_16x16x32_bf16 v[92:95], v[178:181], v[8:11], v[92:95]
	v_mfma_f32_16x16x32_bf16 v[72:75], v[178:181], v[12:15], v[72:75]
	v_mfma_f32_16x16x32_bf16 v[40:43], v[182:185], v[0:3], v[40:43]
	v_mfma_f32_16x16x32_bf16 v[24:27], v[182:185], v[4:7], v[24:27]
	v_mfma_f32_16x16x32_bf16 v[76:79], v[182:185], v[8:11], v[76:79]
	v_mfma_f32_16x16x32_bf16 v[148:151], v[182:185], v[12:15], v[148:151]
	s_waitcnt vmcnt(0)
	s_waitcnt lgkmcnt(0)
	s_barrier
	s_branch .Lgm3_tail
	.p2alignl 6, 3212836864
